# P1 gate epilogue hand-written (bias and rstd loads up front, -log2e folded, 16-wide lock-step sigmoid); P3a gelu chains interleaved
# speedup vs baseline: 1.1041x; 1.0033x over previous
.LBB0_138:
	s_cmp_gt_u32 s94, 7
	s_cbranch_scc0 .LBB0_140
	v_ashrrev_i32_e32 v141, 31, v140
	s_lshl_b32 s12, s94, 8
	s_addk_i32 s12, 0xf800
	v_lshl_add_u64 v[142:143], s[12:13], 2, v[134:135]
	global_load_dwordx4 v[186:189], v[142:143], off
	global_load_dwordx4 v[190:193], v[142:143], off offset:16
	global_load_dwordx4 v[194:197], v[142:143], off offset:32
	global_load_dwordx4 v[198:201], v[142:143], off offset:48
	v_lshlrev_b32_e32 v185, 2, v140
	global_load_dword v202, v185, s[18:19]
	global_load_dword v203, v185, s[18:19] offset:64
	global_load_dword v204, v185, s[18:19] offset:128
	global_load_dword v205, v185, s[18:19] offset:192
	global_load_dword v206, v185, s[18:19] offset:512
	global_load_dword v207, v185, s[18:19] offset:576
	global_load_dword v208, v185, s[18:19] offset:640
	global_load_dword v209, v185, s[18:19] offset:704
	v_lshl_add_u64 v[148:149], v[132:133], 0, s[12:13]
	v_lshlrev_b64 v[146:147], 11, v[140:141]
	v_lshl_add_u64 v[148:149], v[148:149], 0, v[146:147]
	s_mov_b64 s[54:55], 0
	s_waitcnt vmcnt(8)
	v_mul_f32_e32 v186, 0xbfb8aa3b, v186
	v_mul_f32_e32 v187, 0xbfb8aa3b, v187
	v_mul_f32_e32 v188, 0xbfb8aa3b, v188
	v_mul_f32_e32 v189, 0xbfb8aa3b, v189
	v_mul_f32_e32 v190, 0xbfb8aa3b, v190
	v_mul_f32_e32 v191, 0xbfb8aa3b, v191
	v_mul_f32_e32 v192, 0xbfb8aa3b, v192
	v_mul_f32_e32 v193, 0xbfb8aa3b, v193
	v_mul_f32_e32 v194, 0xbfb8aa3b, v194
	v_mul_f32_e32 v195, 0xbfb8aa3b, v195
	v_mul_f32_e32 v196, 0xbfb8aa3b, v196
	v_mul_f32_e32 v197, 0xbfb8aa3b, v197
	v_mul_f32_e32 v198, 0xbfb8aa3b, v198
	v_mul_f32_e32 v199, 0xbfb8aa3b, v199
	v_mul_f32_e32 v200, 0xbfb8aa3b, v200
	v_mul_f32_e32 v201, 0xbfb8aa3b, v201
	s_waitcnt vmcnt(7)
	v_mul_f32_e32 v130, 0xbfb8aa3b, v202
	v_fma_f32 v210, v124, v130, v186
	v_fma_f32 v211, v125, v130, v187
	v_fma_f32 v212, v126, v130, v188
	v_fma_f32 v213, v127, v130, v189
	v_fma_f32 v214, v120, v130, v190
	v_fma_f32 v215, v121, v130, v191
	v_fma_f32 v216, v122, v130, v192
	v_fma_f32 v217, v123, v130, v193
	v_fma_f32 v218, v116, v130, v194
	v_fma_f32 v219, v117, v130, v195
	v_fma_f32 v220, v118, v130, v196
	v_fma_f32 v221, v119, v130, v197
	v_fma_f32 v222, v112, v130, v198
	v_fma_f32 v223, v113, v130, v199
	v_fma_f32 v224, v114, v130, v200
	v_fma_f32 v225, v115, v130, v201
	v_exp_f32_e32 v210, v210
	v_exp_f32_e32 v211, v211
	v_exp_f32_e32 v212, v212
	v_exp_f32_e32 v213, v213
	v_exp_f32_e32 v214, v214
	v_exp_f32_e32 v215, v215
	v_exp_f32_e32 v216, v216
	v_exp_f32_e32 v217, v217
	v_exp_f32_e32 v218, v218
	v_exp_f32_e32 v219, v219
	v_exp_f32_e32 v220, v220
	v_exp_f32_e32 v221, v221
	v_exp_f32_e32 v222, v222
	v_exp_f32_e32 v223, v223
	v_exp_f32_e32 v224, v224
	v_exp_f32_e32 v225, v225
	v_add_f32_e32 v210, 1.0, v210
	v_add_f32_e32 v211, 1.0, v211
	v_add_f32_e32 v212, 1.0, v212
	v_add_f32_e32 v213, 1.0, v213
	v_add_f32_e32 v214, 1.0, v214
	v_add_f32_e32 v215, 1.0, v215
	v_add_f32_e32 v216, 1.0, v216
	v_add_f32_e32 v217, 1.0, v217
	v_add_f32_e32 v218, 1.0, v218
	v_add_f32_e32 v219, 1.0, v219
	v_add_f32_e32 v220, 1.0, v220
	v_add_f32_e32 v221, 1.0, v221
	v_add_f32_e32 v222, 1.0, v222
	v_add_f32_e32 v223, 1.0, v223
	v_add_f32_e32 v224, 1.0, v224
	v_add_f32_e32 v225, 1.0, v225
	v_rcp_f32_e32 v210, v210
	v_rcp_f32_e32 v211, v211
	v_rcp_f32_e32 v212, v212
	v_rcp_f32_e32 v213, v213
	v_rcp_f32_e32 v214, v214
	v_rcp_f32_e32 v215, v215
	v_rcp_f32_e32 v216, v216
	v_rcp_f32_e32 v217, v217
	v_rcp_f32_e32 v218, v218
	v_rcp_f32_e32 v219, v219
	v_rcp_f32_e32 v220, v220
	v_rcp_f32_e32 v221, v221
	v_rcp_f32_e32 v222, v222
	v_rcp_f32_e32 v223, v223
	v_rcp_f32_e32 v224, v224
	v_rcp_f32_e32 v225, v225
	v_fma_f32 v210, v210, s84, 0.5
	v_fma_f32 v211, v211, s84, 0.5
	v_fma_f32 v212, v212, s84, 0.5
	v_fma_f32 v213, v213, s84, 0.5
	v_fma_f32 v214, v214, s84, 0.5
	v_fma_f32 v215, v215, s84, 0.5
	v_fma_f32 v216, v216, s84, 0.5
	v_fma_f32 v217, v217, s84, 0.5
	v_fma_f32 v218, v218, s84, 0.5
	v_fma_f32 v219, v219, s84, 0.5
	v_fma_f32 v220, v220, s84, 0.5
	v_fma_f32 v221, v221, s84, 0.5
	v_fma_f32 v222, v222, s84, 0.5
	v_fma_f32 v223, v223, s84, 0.5
	v_fma_f32 v224, v224, s84, 0.5
	v_fma_f32 v225, v225, s84, 0.5
	v_med3_f32 v210, v210, 1.0, v182
	v_med3_f32 v211, v211, 1.0, v182
	v_med3_f32 v212, v212, 1.0, v182
	v_med3_f32 v213, v213, 1.0, v182
	v_med3_f32 v214, v214, 1.0, v182
	v_med3_f32 v215, v215, 1.0, v182
	v_med3_f32 v216, v216, 1.0, v182
	v_med3_f32 v217, v217, 1.0, v182
	v_med3_f32 v218, v218, 1.0, v182
	v_med3_f32 v219, v219, 1.0, v182
	v_med3_f32 v220, v220, 1.0, v182
	v_med3_f32 v221, v221, 1.0, v182
	v_med3_f32 v222, v222, 1.0, v182
	v_med3_f32 v223, v223, 1.0, v182
	v_med3_f32 v224, v224, 1.0, v182
	v_med3_f32 v225, v225, 1.0, v182
	v_cvt_u32_f32_e32 v210, v210
	v_cvt_u32_f32_e32 v211, v211
	v_cvt_u32_f32_sdwa v212, v212 dst_sel:WORD_1 dst_unused:UNUSED_PAD src0_sel:DWORD
	v_cvt_u32_f32_sdwa v213, v213 dst_sel:BYTE_3 dst_unused:UNUSED_PAD src0_sel:DWORD
	v_cvt_u32_f32_e32 v214, v214
	v_cvt_u32_f32_e32 v215, v215
	v_cvt_u32_f32_sdwa v216, v216 dst_sel:WORD_1 dst_unused:UNUSED_PAD src0_sel:DWORD
	v_cvt_u32_f32_sdwa v217, v217 dst_sel:BYTE_3 dst_unused:UNUSED_PAD src0_sel:DWORD
	v_cvt_u32_f32_e32 v218, v218
	v_cvt_u32_f32_e32 v219, v219
	v_cvt_u32_f32_sdwa v220, v220 dst_sel:WORD_1 dst_unused:UNUSED_PAD src0_sel:DWORD
	v_cvt_u32_f32_sdwa v221, v221 dst_sel:BYTE_3 dst_unused:UNUSED_PAD src0_sel:DWORD
	v_cvt_u32_f32_e32 v222, v222
	v_cvt_u32_f32_e32 v223, v223
	v_cvt_u32_f32_sdwa v224, v224 dst_sel:WORD_1 dst_unused:UNUSED_PAD src0_sel:DWORD
	v_cvt_u32_f32_sdwa v225, v225 dst_sel:BYTE_3 dst_unused:UNUSED_PAD src0_sel:DWORD
	v_lshl_or_b32 v210, v211, 8, v210
	v_lshl_or_b32 v214, v215, 8, v214
	v_lshl_or_b32 v218, v219, 8, v218
	v_lshl_or_b32 v222, v223, 8, v222
	v_or3_b32 v236, v210, v212, v213
	v_or3_b32 v237, v214, v216, v217
	v_or3_b32 v238, v218, v220, v221
	v_or3_b32 v239, v222, v224, v225
	global_store_dwordx4 v[148:149], v[236:239], off nt
	s_waitcnt vmcnt(7)
	v_mul_f32_e32 v130, 0xbfb8aa3b, v203
	v_fma_f32 v210, v108, v130, v186
	v_fma_f32 v211, v109, v130, v187
	v_fma_f32 v212, v110, v130, v188
	v_fma_f32 v213, v111, v130, v189
	v_fma_f32 v214, v104, v130, v190
	v_fma_f32 v215, v105, v130, v191
	v_fma_f32 v216, v106, v130, v192
	v_fma_f32 v217, v107, v130, v193
	v_fma_f32 v218, v100, v130, v194
	v_fma_f32 v219, v101, v130, v195
	v_fma_f32 v220, v102, v130, v196
	v_fma_f32 v221, v103, v130, v197
	v_fma_f32 v222, v96, v130, v198
	v_fma_f32 v223, v97, v130, v199
	v_fma_f32 v224, v98, v130, v200
	v_fma_f32 v225, v99, v130, v201
	v_exp_f32_e32 v210, v210
	v_exp_f32_e32 v211, v211
	v_exp_f32_e32 v212, v212
	v_exp_f32_e32 v213, v213
	v_exp_f32_e32 v214, v214
	v_exp_f32_e32 v215, v215
	v_exp_f32_e32 v216, v216
	v_exp_f32_e32 v217, v217
	v_exp_f32_e32 v218, v218
	v_exp_f32_e32 v219, v219
	v_exp_f32_e32 v220, v220
	v_exp_f32_e32 v221, v221
	v_exp_f32_e32 v222, v222
	v_exp_f32_e32 v223, v223
	v_exp_f32_e32 v224, v224
	v_exp_f32_e32 v225, v225
	v_add_f32_e32 v210, 1.0, v210
	v_add_f32_e32 v211, 1.0, v211
	v_add_f32_e32 v212, 1.0, v212
	v_add_f32_e32 v213, 1.0, v213
	v_add_f32_e32 v214, 1.0, v214
	v_add_f32_e32 v215, 1.0, v215
	v_add_f32_e32 v216, 1.0, v216
	v_add_f32_e32 v217, 1.0, v217
	v_add_f32_e32 v218, 1.0, v218
	v_add_f32_e32 v219, 1.0, v219
	v_add_f32_e32 v220, 1.0, v220
	v_add_f32_e32 v221, 1.0, v221
	v_add_f32_e32 v222, 1.0, v222
	v_add_f32_e32 v223, 1.0, v223
	v_add_f32_e32 v224, 1.0, v224
	v_add_f32_e32 v225, 1.0, v225
	v_rcp_f32_e32 v210, v210
	v_rcp_f32_e32 v211, v211
	v_rcp_f32_e32 v212, v212
	v_rcp_f32_e32 v213, v213
	v_rcp_f32_e32 v214, v214
	v_rcp_f32_e32 v215, v215
	v_rcp_f32_e32 v216, v216
	v_rcp_f32_e32 v217, v217
	v_rcp_f32_e32 v218, v218
	v_rcp_f32_e32 v219, v219
	v_rcp_f32_e32 v220, v220
	v_rcp_f32_e32 v221, v221
	v_rcp_f32_e32 v222, v222
	v_rcp_f32_e32 v223, v223
	v_rcp_f32_e32 v224, v224
	v_rcp_f32_e32 v225, v225
	v_fma_f32 v210, v210, s84, 0.5
	v_fma_f32 v211, v211, s84, 0.5
	v_fma_f32 v212, v212, s84, 0.5
	v_fma_f32 v213, v213, s84, 0.5
	v_fma_f32 v214, v214, s84, 0.5
	v_fma_f32 v215, v215, s84, 0.5
	v_fma_f32 v216, v216, s84, 0.5
	v_fma_f32 v217, v217, s84, 0.5
	v_fma_f32 v218, v218, s84, 0.5
	v_fma_f32 v219, v219, s84, 0.5
	v_fma_f32 v220, v220, s84, 0.5
	v_fma_f32 v221, v221, s84, 0.5
	v_fma_f32 v222, v222, s84, 0.5
	v_fma_f32 v223, v223, s84, 0.5
	v_fma_f32 v224, v224, s84, 0.5
	v_fma_f32 v225, v225, s84, 0.5
	v_med3_f32 v210, v210, 1.0, v182
	v_med3_f32 v211, v211, 1.0, v182
	v_med3_f32 v212, v212, 1.0, v182
	v_med3_f32 v213, v213, 1.0, v182
	v_med3_f32 v214, v214, 1.0, v182
	v_med3_f32 v215, v215, 1.0, v182
	v_med3_f32 v216, v216, 1.0, v182
	v_med3_f32 v217, v217, 1.0, v182
	v_med3_f32 v218, v218, 1.0, v182
	v_med3_f32 v219, v219, 1.0, v182
	v_med3_f32 v220, v220, 1.0, v182
	v_med3_f32 v221, v221, 1.0, v182
	v_med3_f32 v222, v222, 1.0, v182
	v_med3_f32 v223, v223, 1.0, v182
	v_med3_f32 v224, v224, 1.0, v182
	v_med3_f32 v225, v225, 1.0, v182
	v_cvt_u32_f32_e32 v210, v210
	v_cvt_u32_f32_e32 v211, v211
	v_cvt_u32_f32_sdwa v212, v212 dst_sel:WORD_1 dst_unused:UNUSED_PAD src0_sel:DWORD
	v_cvt_u32_f32_sdwa v213, v213 dst_sel:BYTE_3 dst_unused:UNUSED_PAD src0_sel:DWORD
	v_cvt_u32_f32_e32 v214, v214
	v_cvt_u32_f32_e32 v215, v215
	v_cvt_u32_f32_sdwa v216, v216 dst_sel:WORD_1 dst_unused:UNUSED_PAD src0_sel:DWORD
	v_cvt_u32_f32_sdwa v217, v217 dst_sel:BYTE_3 dst_unused:UNUSED_PAD src0_sel:DWORD
	v_cvt_u32_f32_e32 v218, v218
	v_cvt_u32_f32_e32 v219, v219
	v_cvt_u32_f32_sdwa v220, v220 dst_sel:WORD_1 dst_unused:UNUSED_PAD src0_sel:DWORD
	v_cvt_u32_f32_sdwa v221, v221 dst_sel:BYTE_3 dst_unused:UNUSED_PAD src0_sel:DWORD
	v_cvt_u32_f32_e32 v222, v222
	v_cvt_u32_f32_e32 v223, v223
	v_cvt_u32_f32_sdwa v224, v224 dst_sel:WORD_1 dst_unused:UNUSED_PAD src0_sel:DWORD
	v_cvt_u32_f32_sdwa v225, v225 dst_sel:BYTE_3 dst_unused:UNUSED_PAD src0_sel:DWORD
	v_lshl_or_b32 v210, v211, 8, v210
	v_lshl_or_b32 v214, v215, 8, v214
	v_lshl_or_b32 v218, v219, 8, v218
	v_lshl_or_b32 v222, v223, 8, v222
	v_or3_b32 v236, v210, v212, v213
	v_or3_b32 v237, v214, v216, v217
	v_or3_b32 v238, v218, v220, v221
	v_or3_b32 v239, v222, v224, v225
	v_add_co_u32_e32 v146, vcc, 0x8000, v148
	s_nop 1
	v_addc_co_u32_e32 v147, vcc, 0, v149, vcc
	global_store_dwordx4 v[146:147], v[236:239], off nt
	s_waitcnt vmcnt(7)
	v_mul_f32_e32 v130, 0xbfb8aa3b, v204
	v_fma_f32 v210, v92, v130, v186
	v_fma_f32 v211, v93, v130, v187
	v_fma_f32 v212, v94, v130, v188
	v_fma_f32 v213, v95, v130, v189
	v_fma_f32 v214, v88, v130, v190
	v_fma_f32 v215, v89, v130, v191
	v_fma_f32 v216, v90, v130, v192
	v_fma_f32 v217, v91, v130, v193
	v_fma_f32 v218, v84, v130, v194
	v_fma_f32 v219, v85, v130, v195
	v_fma_f32 v220, v86, v130, v196
	v_fma_f32 v221, v87, v130, v197
	v_fma_f32 v222, v80, v130, v198
	v_fma_f32 v223, v81, v130, v199
	v_fma_f32 v224, v82, v130, v200
	v_fma_f32 v225, v83, v130, v201
	v_exp_f32_e32 v210, v210
	v_exp_f32_e32 v211, v211
	v_exp_f32_e32 v212, v212
	v_exp_f32_e32 v213, v213
	v_exp_f32_e32 v214, v214
	v_exp_f32_e32 v215, v215
	v_exp_f32_e32 v216, v216
	v_exp_f32_e32 v217, v217
	v_exp_f32_e32 v218, v218
	v_exp_f32_e32 v219, v219
	v_exp_f32_e32 v220, v220
	v_exp_f32_e32 v221, v221
	v_exp_f32_e32 v222, v222
	v_exp_f32_e32 v223, v223
	v_exp_f32_e32 v224, v224
	v_exp_f32_e32 v225, v225
	v_add_f32_e32 v210, 1.0, v210
	v_add_f32_e32 v211, 1.0, v211
	v_add_f32_e32 v212, 1.0, v212
	v_add_f32_e32 v213, 1.0, v213
	v_add_f32_e32 v214, 1.0, v214
	v_add_f32_e32 v215, 1.0, v215
	v_add_f32_e32 v216, 1.0, v216
	v_add_f32_e32 v217, 1.0, v217
	v_add_f32_e32 v218, 1.0, v218
	v_add_f32_e32 v219, 1.0, v219
	v_add_f32_e32 v220, 1.0, v220
	v_add_f32_e32 v221, 1.0, v221
	v_add_f32_e32 v222, 1.0, v222
	v_add_f32_e32 v223, 1.0, v223
	v_add_f32_e32 v224, 1.0, v224
	v_add_f32_e32 v225, 1.0, v225
	v_rcp_f32_e32 v210, v210
	v_rcp_f32_e32 v211, v211
	v_rcp_f32_e32 v212, v212
	v_rcp_f32_e32 v213, v213
	v_rcp_f32_e32 v214, v214
	v_rcp_f32_e32 v215, v215
	v_rcp_f32_e32 v216, v216
	v_rcp_f32_e32 v217, v217
	v_rcp_f32_e32 v218, v218
	v_rcp_f32_e32 v219, v219
	v_rcp_f32_e32 v220, v220
	v_rcp_f32_e32 v221, v221
	v_rcp_f32_e32 v222, v222
	v_rcp_f32_e32 v223, v223
	v_rcp_f32_e32 v224, v224
	v_rcp_f32_e32 v225, v225
	v_fma_f32 v210, v210, s84, 0.5
	v_fma_f32 v211, v211, s84, 0.5
	v_fma_f32 v212, v212, s84, 0.5
	v_fma_f32 v213, v213, s84, 0.5
	v_fma_f32 v214, v214, s84, 0.5
	v_fma_f32 v215, v215, s84, 0.5
	v_fma_f32 v216, v216, s84, 0.5
	v_fma_f32 v217, v217, s84, 0.5
	v_fma_f32 v218, v218, s84, 0.5
	v_fma_f32 v219, v219, s84, 0.5
	v_fma_f32 v220, v220, s84, 0.5
	v_fma_f32 v221, v221, s84, 0.5
	v_fma_f32 v222, v222, s84, 0.5
	v_fma_f32 v223, v223, s84, 0.5
	v_fma_f32 v224, v224, s84, 0.5
	v_fma_f32 v225, v225, s84, 0.5
	v_med3_f32 v210, v210, 1.0, v182
	v_med3_f32 v211, v211, 1.0, v182
	v_med3_f32 v212, v212, 1.0, v182
	v_med3_f32 v213, v213, 1.0, v182
	v_med3_f32 v214, v214, 1.0, v182
	v_med3_f32 v215, v215, 1.0, v182
	v_med3_f32 v216, v216, 1.0, v182
	v_med3_f32 v217, v217, 1.0, v182
	v_med3_f32 v218, v218, 1.0, v182
	v_med3_f32 v219, v219, 1.0, v182
	v_med3_f32 v220, v220, 1.0, v182
	v_med3_f32 v221, v221, 1.0, v182
	v_med3_f32 v222, v222, 1.0, v182
	v_med3_f32 v223, v223, 1.0, v182
	v_med3_f32 v224, v224, 1.0, v182
	v_med3_f32 v225, v225, 1.0, v182
	v_cvt_u32_f32_e32 v210, v210
	v_cvt_u32_f32_e32 v211, v211
	v_cvt_u32_f32_sdwa v212, v212 dst_sel:WORD_1 dst_unused:UNUSED_PAD src0_sel:DWORD
	v_cvt_u32_f32_sdwa v213, v213 dst_sel:BYTE_3 dst_unused:UNUSED_PAD src0_sel:DWORD
	v_cvt_u32_f32_e32 v214, v214
	v_cvt_u32_f32_e32 v215, v215
	v_cvt_u32_f32_sdwa v216, v216 dst_sel:WORD_1 dst_unused:UNUSED_PAD src0_sel:DWORD
	v_cvt_u32_f32_sdwa v217, v217 dst_sel:BYTE_3 dst_unused:UNUSED_PAD src0_sel:DWORD
	v_cvt_u32_f32_e32 v218, v218
	v_cvt_u32_f32_e32 v219, v219
	v_cvt_u32_f32_sdwa v220, v220 dst_sel:WORD_1 dst_unused:UNUSED_PAD src0_sel:DWORD
	v_cvt_u32_f32_sdwa v221, v221 dst_sel:BYTE_3 dst_unused:UNUSED_PAD src0_sel:DWORD
	v_cvt_u32_f32_e32 v222, v222
	v_cvt_u32_f32_e32 v223, v223
	v_cvt_u32_f32_sdwa v224, v224 dst_sel:WORD_1 dst_unused:UNUSED_PAD src0_sel:DWORD
	v_cvt_u32_f32_sdwa v225, v225 dst_sel:BYTE_3 dst_unused:UNUSED_PAD src0_sel:DWORD
	v_lshl_or_b32 v210, v211, 8, v210
	v_lshl_or_b32 v214, v215, 8, v214
	v_lshl_or_b32 v218, v219, 8, v218
	v_lshl_or_b32 v222, v223, 8, v222
	v_or3_b32 v236, v210, v212, v213
	v_or3_b32 v237, v214, v216, v217
	v_or3_b32 v238, v218, v220, v221
	v_or3_b32 v239, v222, v224, v225
	v_add_co_u32_e32 v146, vcc, 0x10000, v148
	s_nop 1
	v_addc_co_u32_e32 v147, vcc, 0, v149, vcc
	global_store_dwordx4 v[146:147], v[236:239], off nt
	s_waitcnt vmcnt(7)
	v_mul_f32_e32 v130, 0xbfb8aa3b, v205
	v_fma_f32 v210, v76, v130, v186
	v_fma_f32 v211, v77, v130, v187
	v_fma_f32 v212, v78, v130, v188
	v_fma_f32 v213, v79, v130, v189
	v_fma_f32 v214, v72, v130, v190
	v_fma_f32 v215, v73, v130, v191
	v_fma_f32 v216, v74, v130, v192
	v_fma_f32 v217, v75, v130, v193
	v_fma_f32 v218, v68, v130, v194
	v_fma_f32 v219, v69, v130, v195
	v_fma_f32 v220, v70, v130, v196
	v_fma_f32 v221, v71, v130, v197
	v_fma_f32 v222, v64, v130, v198
	v_fma_f32 v223, v65, v130, v199
	v_fma_f32 v224, v66, v130, v200
	v_fma_f32 v225, v67, v130, v201
	v_exp_f32_e32 v210, v210
	v_exp_f32_e32 v211, v211
	v_exp_f32_e32 v212, v212
	v_exp_f32_e32 v213, v213
	v_exp_f32_e32 v214, v214
	v_exp_f32_e32 v215, v215
	v_exp_f32_e32 v216, v216
	v_exp_f32_e32 v217, v217
	v_exp_f32_e32 v218, v218
	v_exp_f32_e32 v219, v219
	v_exp_f32_e32 v220, v220
	v_exp_f32_e32 v221, v221
	v_exp_f32_e32 v222, v222
	v_exp_f32_e32 v223, v223
	v_exp_f32_e32 v224, v224
	v_exp_f32_e32 v225, v225
	v_add_f32_e32 v210, 1.0, v210
	v_add_f32_e32 v211, 1.0, v211
	v_add_f32_e32 v212, 1.0, v212
	v_add_f32_e32 v213, 1.0, v213
	v_add_f32_e32 v214, 1.0, v214
	v_add_f32_e32 v215, 1.0, v215
	v_add_f32_e32 v216, 1.0, v216
	v_add_f32_e32 v217, 1.0, v217
	v_add_f32_e32 v218, 1.0, v218
	v_add_f32_e32 v219, 1.0, v219
	v_add_f32_e32 v220, 1.0, v220
	v_add_f32_e32 v221, 1.0, v221
	v_add_f32_e32 v222, 1.0, v222
	v_add_f32_e32 v223, 1.0, v223
	v_add_f32_e32 v224, 1.0, v224
	v_add_f32_e32 v225, 1.0, v225
	v_rcp_f32_e32 v210, v210
	v_rcp_f32_e32 v211, v211
	v_rcp_f32_e32 v212, v212
	v_rcp_f32_e32 v213, v213
	v_rcp_f32_e32 v214, v214
	v_rcp_f32_e32 v215, v215
	v_rcp_f32_e32 v216, v216
	v_rcp_f32_e32 v217, v217
	v_rcp_f32_e32 v218, v218
	v_rcp_f32_e32 v219, v219
	v_rcp_f32_e32 v220, v220
	v_rcp_f32_e32 v221, v221
	v_rcp_f32_e32 v222, v222
	v_rcp_f32_e32 v223, v223
	v_rcp_f32_e32 v224, v224
	v_rcp_f32_e32 v225, v225
	v_fma_f32 v210, v210, s84, 0.5
	v_fma_f32 v211, v211, s84, 0.5
	v_fma_f32 v212, v212, s84, 0.5
	v_fma_f32 v213, v213, s84, 0.5
	v_fma_f32 v214, v214, s84, 0.5
	v_fma_f32 v215, v215, s84, 0.5
	v_fma_f32 v216, v216, s84, 0.5
	v_fma_f32 v217, v217, s84, 0.5
	v_fma_f32 v218, v218, s84, 0.5
	v_fma_f32 v219, v219, s84, 0.5
	v_fma_f32 v220, v220, s84, 0.5
	v_fma_f32 v221, v221, s84, 0.5
	v_fma_f32 v222, v222, s84, 0.5
	v_fma_f32 v223, v223, s84, 0.5
	v_fma_f32 v224, v224, s84, 0.5
	v_fma_f32 v225, v225, s84, 0.5
	v_med3_f32 v210, v210, 1.0, v182
	v_med3_f32 v211, v211, 1.0, v182
	v_med3_f32 v212, v212, 1.0, v182
	v_med3_f32 v213, v213, 1.0, v182
	v_med3_f32 v214, v214, 1.0, v182
	v_med3_f32 v215, v215, 1.0, v182
	v_med3_f32 v216, v216, 1.0, v182
	v_med3_f32 v217, v217, 1.0, v182
	v_med3_f32 v218, v218, 1.0, v182
	v_med3_f32 v219, v219, 1.0, v182
	v_med3_f32 v220, v220, 1.0, v182
	v_med3_f32 v221, v221, 1.0, v182
	v_med3_f32 v222, v222, 1.0, v182
	v_med3_f32 v223, v223, 1.0, v182
	v_med3_f32 v224, v224, 1.0, v182
	v_med3_f32 v225, v225, 1.0, v182
	v_cvt_u32_f32_e32 v210, v210
	v_cvt_u32_f32_e32 v211, v211
	v_cvt_u32_f32_sdwa v212, v212 dst_sel:WORD_1 dst_unused:UNUSED_PAD src0_sel:DWORD
	v_cvt_u32_f32_sdwa v213, v213 dst_sel:BYTE_3 dst_unused:UNUSED_PAD src0_sel:DWORD
	v_cvt_u32_f32_e32 v214, v214
	v_cvt_u32_f32_e32 v215, v215
	v_cvt_u32_f32_sdwa v216, v216 dst_sel:WORD_1 dst_unused:UNUSED_PAD src0_sel:DWORD
	v_cvt_u32_f32_sdwa v217, v217 dst_sel:BYTE_3 dst_unused:UNUSED_PAD src0_sel:DWORD
	v_cvt_u32_f32_e32 v218, v218
	v_cvt_u32_f32_e32 v219, v219
	v_cvt_u32_f32_sdwa v220, v220 dst_sel:WORD_1 dst_unused:UNUSED_PAD src0_sel:DWORD
	v_cvt_u32_f32_sdwa v221, v221 dst_sel:BYTE_3 dst_unused:UNUSED_PAD src0_sel:DWORD
	v_cvt_u32_f32_e32 v222, v222
	v_cvt_u32_f32_e32 v223, v223
	v_cvt_u32_f32_sdwa v224, v224 dst_sel:WORD_1 dst_unused:UNUSED_PAD src0_sel:DWORD
	v_cvt_u32_f32_sdwa v225, v225 dst_sel:BYTE_3 dst_unused:UNUSED_PAD src0_sel:DWORD
	v_lshl_or_b32 v210, v211, 8, v210
	v_lshl_or_b32 v214, v215, 8, v214
	v_lshl_or_b32 v218, v219, 8, v218
	v_lshl_or_b32 v222, v223, 8, v222
	v_or3_b32 v236, v210, v212, v213
	v_or3_b32 v237, v214, v216, v217
	v_or3_b32 v238, v218, v220, v221
	v_or3_b32 v239, v222, v224, v225
	v_add_co_u32_e32 v146, vcc, 0x18000, v148
	s_nop 1
	v_addc_co_u32_e32 v147, vcc, 0, v149, vcc
	global_store_dwordx4 v[146:147], v[236:239], off nt
	s_waitcnt vmcnt(7)
	v_mul_f32_e32 v130, 0xbfb8aa3b, v206
	v_fma_f32 v210, v60, v130, v186
	v_fma_f32 v211, v61, v130, v187
	v_fma_f32 v212, v62, v130, v188
	v_fma_f32 v213, v63, v130, v189
	v_fma_f32 v214, v56, v130, v190
	v_fma_f32 v215, v57, v130, v191
	v_fma_f32 v216, v58, v130, v192
	v_fma_f32 v217, v59, v130, v193
	v_fma_f32 v218, v52, v130, v194
	v_fma_f32 v219, v53, v130, v195
	v_fma_f32 v220, v54, v130, v196
	v_fma_f32 v221, v55, v130, v197
	v_fma_f32 v222, v48, v130, v198
	v_fma_f32 v223, v49, v130, v199
	v_fma_f32 v224, v50, v130, v200
	v_fma_f32 v225, v51, v130, v201
	v_exp_f32_e32 v210, v210
	v_exp_f32_e32 v211, v211
	v_exp_f32_e32 v212, v212
	v_exp_f32_e32 v213, v213
	v_exp_f32_e32 v214, v214
	v_exp_f32_e32 v215, v215
	v_exp_f32_e32 v216, v216
	v_exp_f32_e32 v217, v217
	v_exp_f32_e32 v218, v218
	v_exp_f32_e32 v219, v219
	v_exp_f32_e32 v220, v220
	v_exp_f32_e32 v221, v221
	v_exp_f32_e32 v222, v222
	v_exp_f32_e32 v223, v223
	v_exp_f32_e32 v224, v224
	v_exp_f32_e32 v225, v225
	v_add_f32_e32 v210, 1.0, v210
	v_add_f32_e32 v211, 1.0, v211
	v_add_f32_e32 v212, 1.0, v212
	v_add_f32_e32 v213, 1.0, v213
	v_add_f32_e32 v214, 1.0, v214
	v_add_f32_e32 v215, 1.0, v215
	v_add_f32_e32 v216, 1.0, v216
	v_add_f32_e32 v217, 1.0, v217
	v_add_f32_e32 v218, 1.0, v218
	v_add_f32_e32 v219, 1.0, v219
	v_add_f32_e32 v220, 1.0, v220
	v_add_f32_e32 v221, 1.0, v221
	v_add_f32_e32 v222, 1.0, v222
	v_add_f32_e32 v223, 1.0, v223
	v_add_f32_e32 v224, 1.0, v224
	v_add_f32_e32 v225, 1.0, v225
	v_rcp_f32_e32 v210, v210
	v_rcp_f32_e32 v211, v211
	v_rcp_f32_e32 v212, v212
	v_rcp_f32_e32 v213, v213
	v_rcp_f32_e32 v214, v214
	v_rcp_f32_e32 v215, v215
	v_rcp_f32_e32 v216, v216
	v_rcp_f32_e32 v217, v217
	v_rcp_f32_e32 v218, v218
	v_rcp_f32_e32 v219, v219
	v_rcp_f32_e32 v220, v220
	v_rcp_f32_e32 v221, v221
	v_rcp_f32_e32 v222, v222
	v_rcp_f32_e32 v223, v223
	v_rcp_f32_e32 v224, v224
	v_rcp_f32_e32 v225, v225
	v_fma_f32 v210, v210, s84, 0.5
	v_fma_f32 v211, v211, s84, 0.5
	v_fma_f32 v212, v212, s84, 0.5
	v_fma_f32 v213, v213, s84, 0.5
	v_fma_f32 v214, v214, s84, 0.5
	v_fma_f32 v215, v215, s84, 0.5
	v_fma_f32 v216, v216, s84, 0.5
	v_fma_f32 v217, v217, s84, 0.5
	v_fma_f32 v218, v218, s84, 0.5
	v_fma_f32 v219, v219, s84, 0.5
	v_fma_f32 v220, v220, s84, 0.5
	v_fma_f32 v221, v221, s84, 0.5
	v_fma_f32 v222, v222, s84, 0.5
	v_fma_f32 v223, v223, s84, 0.5
	v_fma_f32 v224, v224, s84, 0.5
	v_fma_f32 v225, v225, s84, 0.5
	v_med3_f32 v210, v210, 1.0, v182
	v_med3_f32 v211, v211, 1.0, v182
	v_med3_f32 v212, v212, 1.0, v182
	v_med3_f32 v213, v213, 1.0, v182
	v_med3_f32 v214, v214, 1.0, v182
	v_med3_f32 v215, v215, 1.0, v182
	v_med3_f32 v216, v216, 1.0, v182
	v_med3_f32 v217, v217, 1.0, v182
	v_med3_f32 v218, v218, 1.0, v182
	v_med3_f32 v219, v219, 1.0, v182
	v_med3_f32 v220, v220, 1.0, v182
	v_med3_f32 v221, v221, 1.0, v182
	v_med3_f32 v222, v222, 1.0, v182
	v_med3_f32 v223, v223, 1.0, v182
	v_med3_f32 v224, v224, 1.0, v182
	v_med3_f32 v225, v225, 1.0, v182
	v_cvt_u32_f32_e32 v210, v210
	v_cvt_u32_f32_e32 v211, v211
	v_cvt_u32_f32_sdwa v212, v212 dst_sel:WORD_1 dst_unused:UNUSED_PAD src0_sel:DWORD
	v_cvt_u32_f32_sdwa v213, v213 dst_sel:BYTE_3 dst_unused:UNUSED_PAD src0_sel:DWORD
	v_cvt_u32_f32_e32 v214, v214
	v_cvt_u32_f32_e32 v215, v215
	v_cvt_u32_f32_sdwa v216, v216 dst_sel:WORD_1 dst_unused:UNUSED_PAD src0_sel:DWORD
	v_cvt_u32_f32_sdwa v217, v217 dst_sel:BYTE_3 dst_unused:UNUSED_PAD src0_sel:DWORD
	v_cvt_u32_f32_e32 v218, v218
	v_cvt_u32_f32_e32 v219, v219
	v_cvt_u32_f32_sdwa v220, v220 dst_sel:WORD_1 dst_unused:UNUSED_PAD src0_sel:DWORD
	v_cvt_u32_f32_sdwa v221, v221 dst_sel:BYTE_3 dst_unused:UNUSED_PAD src0_sel:DWORD
	v_cvt_u32_f32_e32 v222, v222
	v_cvt_u32_f32_e32 v223, v223
	v_cvt_u32_f32_sdwa v224, v224 dst_sel:WORD_1 dst_unused:UNUSED_PAD src0_sel:DWORD
	v_cvt_u32_f32_sdwa v225, v225 dst_sel:BYTE_3 dst_unused:UNUSED_PAD src0_sel:DWORD
	v_lshl_or_b32 v210, v211, 8, v210
	v_lshl_or_b32 v214, v215, 8, v214
	v_lshl_or_b32 v218, v219, 8, v218
	v_lshl_or_b32 v222, v223, 8, v222
	v_or3_b32 v236, v210, v212, v213
	v_or3_b32 v237, v214, v216, v217
	v_or3_b32 v238, v218, v220, v221
	v_or3_b32 v239, v222, v224, v225
	v_add_co_u32_e32 v146, vcc, 0x40000, v148
	s_nop 1
	v_addc_co_u32_e32 v147, vcc, 0, v149, vcc
	global_store_dwordx4 v[146:147], v[236:239], off nt
	s_waitcnt vmcnt(7)
	v_mul_f32_e32 v130, 0xbfb8aa3b, v207
	v_fma_f32 v210, v44, v130, v186
	v_fma_f32 v211, v45, v130, v187
	v_fma_f32 v212, v46, v130, v188
	v_fma_f32 v213, v47, v130, v189
	v_fma_f32 v214, v40, v130, v190
	v_fma_f32 v215, v41, v130, v191
	v_fma_f32 v216, v42, v130, v192
	v_fma_f32 v217, v43, v130, v193
	v_fma_f32 v218, v36, v130, v194
	v_fma_f32 v219, v37, v130, v195
	v_fma_f32 v220, v38, v130, v196
	v_fma_f32 v221, v39, v130, v197
	v_fma_f32 v222, v32, v130, v198
	v_fma_f32 v223, v33, v130, v199
	v_fma_f32 v224, v34, v130, v200
	v_fma_f32 v225, v35, v130, v201
	v_exp_f32_e32 v210, v210
	v_exp_f32_e32 v211, v211
	v_exp_f32_e32 v212, v212
	v_exp_f32_e32 v213, v213
	v_exp_f32_e32 v214, v214
	v_exp_f32_e32 v215, v215
	v_exp_f32_e32 v216, v216
	v_exp_f32_e32 v217, v217
	v_exp_f32_e32 v218, v218
	v_exp_f32_e32 v219, v219
	v_exp_f32_e32 v220, v220
	v_exp_f32_e32 v221, v221
	v_exp_f32_e32 v222, v222
	v_exp_f32_e32 v223, v223
	v_exp_f32_e32 v224, v224
	v_exp_f32_e32 v225, v225
	v_add_f32_e32 v210, 1.0, v210
	v_add_f32_e32 v211, 1.0, v211
	v_add_f32_e32 v212, 1.0, v212
	v_add_f32_e32 v213, 1.0, v213
	v_add_f32_e32 v214, 1.0, v214
	v_add_f32_e32 v215, 1.0, v215
	v_add_f32_e32 v216, 1.0, v216
	v_add_f32_e32 v217, 1.0, v217
	v_add_f32_e32 v218, 1.0, v218
	v_add_f32_e32 v219, 1.0, v219
	v_add_f32_e32 v220, 1.0, v220
	v_add_f32_e32 v221, 1.0, v221
	v_add_f32_e32 v222, 1.0, v222
	v_add_f32_e32 v223, 1.0, v223
	v_add_f32_e32 v224, 1.0, v224
	v_add_f32_e32 v225, 1.0, v225
	v_rcp_f32_e32 v210, v210
	v_rcp_f32_e32 v211, v211
	v_rcp_f32_e32 v212, v212
	v_rcp_f32_e32 v213, v213
	v_rcp_f32_e32 v214, v214
	v_rcp_f32_e32 v215, v215
	v_rcp_f32_e32 v216, v216
	v_rcp_f32_e32 v217, v217
	v_rcp_f32_e32 v218, v218
	v_rcp_f32_e32 v219, v219
	v_rcp_f32_e32 v220, v220
	v_rcp_f32_e32 v221, v221
	v_rcp_f32_e32 v222, v222
	v_rcp_f32_e32 v223, v223
	v_rcp_f32_e32 v224, v224
	v_rcp_f32_e32 v225, v225
	v_fma_f32 v210, v210, s84, 0.5
	v_fma_f32 v211, v211, s84, 0.5
	v_fma_f32 v212, v212, s84, 0.5
	v_fma_f32 v213, v213, s84, 0.5
	v_fma_f32 v214, v214, s84, 0.5
	v_fma_f32 v215, v215, s84, 0.5
	v_fma_f32 v216, v216, s84, 0.5
	v_fma_f32 v217, v217, s84, 0.5
	v_fma_f32 v218, v218, s84, 0.5
	v_fma_f32 v219, v219, s84, 0.5
	v_fma_f32 v220, v220, s84, 0.5
	v_fma_f32 v221, v221, s84, 0.5
	v_fma_f32 v222, v222, s84, 0.5
	v_fma_f32 v223, v223, s84, 0.5
	v_fma_f32 v224, v224, s84, 0.5
	v_fma_f32 v225, v225, s84, 0.5
	v_med3_f32 v210, v210, 1.0, v182
	v_med3_f32 v211, v211, 1.0, v182
	v_med3_f32 v212, v212, 1.0, v182
	v_med3_f32 v213, v213, 1.0, v182
	v_med3_f32 v214, v214, 1.0, v182
	v_med3_f32 v215, v215, 1.0, v182
	v_med3_f32 v216, v216, 1.0, v182
	v_med3_f32 v217, v217, 1.0, v182
	v_med3_f32 v218, v218, 1.0, v182
	v_med3_f32 v219, v219, 1.0, v182
	v_med3_f32 v220, v220, 1.0, v182
	v_med3_f32 v221, v221, 1.0, v182
	v_med3_f32 v222, v222, 1.0, v182
	v_med3_f32 v223, v223, 1.0, v182
	v_med3_f32 v224, v224, 1.0, v182
	v_med3_f32 v225, v225, 1.0, v182
	v_cvt_u32_f32_e32 v210, v210
	v_cvt_u32_f32_e32 v211, v211
	v_cvt_u32_f32_sdwa v212, v212 dst_sel:WORD_1 dst_unused:UNUSED_PAD src0_sel:DWORD
	v_cvt_u32_f32_sdwa v213, v213 dst_sel:BYTE_3 dst_unused:UNUSED_PAD src0_sel:DWORD
	v_cvt_u32_f32_e32 v214, v214
	v_cvt_u32_f32_e32 v215, v215
	v_cvt_u32_f32_sdwa v216, v216 dst_sel:WORD_1 dst_unused:UNUSED_PAD src0_sel:DWORD
	v_cvt_u32_f32_sdwa v217, v217 dst_sel:BYTE_3 dst_unused:UNUSED_PAD src0_sel:DWORD
	v_cvt_u32_f32_e32 v218, v218
	v_cvt_u32_f32_e32 v219, v219
	v_cvt_u32_f32_sdwa v220, v220 dst_sel:WORD_1 dst_unused:UNUSED_PAD src0_sel:DWORD
	v_cvt_u32_f32_sdwa v221, v221 dst_sel:BYTE_3 dst_unused:UNUSED_PAD src0_sel:DWORD
	v_cvt_u32_f32_e32 v222, v222
	v_cvt_u32_f32_e32 v223, v223
	v_cvt_u32_f32_sdwa v224, v224 dst_sel:WORD_1 dst_unused:UNUSED_PAD src0_sel:DWORD
	v_cvt_u32_f32_sdwa v225, v225 dst_sel:BYTE_3 dst_unused:UNUSED_PAD src0_sel:DWORD
	v_lshl_or_b32 v210, v211, 8, v210
	v_lshl_or_b32 v214, v215, 8, v214
	v_lshl_or_b32 v218, v219, 8, v218
	v_lshl_or_b32 v222, v223, 8, v222
	v_or3_b32 v236, v210, v212, v213
	v_or3_b32 v237, v214, v216, v217
	v_or3_b32 v238, v218, v220, v221
	v_or3_b32 v239, v222, v224, v225
	v_add_co_u32_e32 v146, vcc, 0x48000, v148
	s_nop 1
	v_addc_co_u32_e32 v147, vcc, 0, v149, vcc
	global_store_dwordx4 v[146:147], v[236:239], off nt
	s_waitcnt vmcnt(7)
	v_mul_f32_e32 v130, 0xbfb8aa3b, v208
	v_fma_f32 v210, v28, v130, v186
	v_fma_f32 v211, v29, v130, v187
	v_fma_f32 v212, v30, v130, v188
	v_fma_f32 v213, v31, v130, v189
	v_fma_f32 v214, v24, v130, v190
	v_fma_f32 v215, v25, v130, v191
	v_fma_f32 v216, v26, v130, v192
	v_fma_f32 v217, v27, v130, v193
	v_fma_f32 v218, v20, v130, v194
	v_fma_f32 v219, v21, v130, v195
	v_fma_f32 v220, v22, v130, v196
	v_fma_f32 v221, v23, v130, v197
	v_fma_f32 v222, v16, v130, v198
	v_fma_f32 v223, v17, v130, v199
	v_fma_f32 v224, v18, v130, v200
	v_fma_f32 v225, v19, v130, v201
	v_exp_f32_e32 v210, v210
	v_exp_f32_e32 v211, v211
	v_exp_f32_e32 v212, v212
	v_exp_f32_e32 v213, v213
	v_exp_f32_e32 v214, v214
	v_exp_f32_e32 v215, v215
	v_exp_f32_e32 v216, v216
	v_exp_f32_e32 v217, v217
	v_exp_f32_e32 v218, v218
	v_exp_f32_e32 v219, v219
	v_exp_f32_e32 v220, v220
	v_exp_f32_e32 v221, v221
	v_exp_f32_e32 v222, v222
	v_exp_f32_e32 v223, v223
	v_exp_f32_e32 v224, v224
	v_exp_f32_e32 v225, v225
	v_add_f32_e32 v210, 1.0, v210
	v_add_f32_e32 v211, 1.0, v211
	v_add_f32_e32 v212, 1.0, v212
	v_add_f32_e32 v213, 1.0, v213
	v_add_f32_e32 v214, 1.0, v214
	v_add_f32_e32 v215, 1.0, v215
	v_add_f32_e32 v216, 1.0, v216
	v_add_f32_e32 v217, 1.0, v217
	v_add_f32_e32 v218, 1.0, v218
	v_add_f32_e32 v219, 1.0, v219
	v_add_f32_e32 v220, 1.0, v220
	v_add_f32_e32 v221, 1.0, v221
	v_add_f32_e32 v222, 1.0, v222
	v_add_f32_e32 v223, 1.0, v223
	v_add_f32_e32 v224, 1.0, v224
	v_add_f32_e32 v225, 1.0, v225
	v_rcp_f32_e32 v210, v210
	v_rcp_f32_e32 v211, v211
	v_rcp_f32_e32 v212, v212
	v_rcp_f32_e32 v213, v213
	v_rcp_f32_e32 v214, v214
	v_rcp_f32_e32 v215, v215
	v_rcp_f32_e32 v216, v216
	v_rcp_f32_e32 v217, v217
	v_rcp_f32_e32 v218, v218
	v_rcp_f32_e32 v219, v219
	v_rcp_f32_e32 v220, v220
	v_rcp_f32_e32 v221, v221
	v_rcp_f32_e32 v222, v222
	v_rcp_f32_e32 v223, v223
	v_rcp_f32_e32 v224, v224
	v_rcp_f32_e32 v225, v225
	v_fma_f32 v210, v210, s84, 0.5
	v_fma_f32 v211, v211, s84, 0.5
	v_fma_f32 v212, v212, s84, 0.5
	v_fma_f32 v213, v213, s84, 0.5
	v_fma_f32 v214, v214, s84, 0.5
	v_fma_f32 v215, v215, s84, 0.5
	v_fma_f32 v216, v216, s84, 0.5
	v_fma_f32 v217, v217, s84, 0.5
	v_fma_f32 v218, v218, s84, 0.5
	v_fma_f32 v219, v219, s84, 0.5
	v_fma_f32 v220, v220, s84, 0.5
	v_fma_f32 v221, v221, s84, 0.5
	v_fma_f32 v222, v222, s84, 0.5
	v_fma_f32 v223, v223, s84, 0.5
	v_fma_f32 v224, v224, s84, 0.5
	v_fma_f32 v225, v225, s84, 0.5
	v_med3_f32 v210, v210, 1.0, v182
	v_med3_f32 v211, v211, 1.0, v182
	v_med3_f32 v212, v212, 1.0, v182
	v_med3_f32 v213, v213, 1.0, v182
	v_med3_f32 v214, v214, 1.0, v182
	v_med3_f32 v215, v215, 1.0, v182
	v_med3_f32 v216, v216, 1.0, v182
	v_med3_f32 v217, v217, 1.0, v182
	v_med3_f32 v218, v218, 1.0, v182
	v_med3_f32 v219, v219, 1.0, v182
	v_med3_f32 v220, v220, 1.0, v182
	v_med3_f32 v221, v221, 1.0, v182
	v_med3_f32 v222, v222, 1.0, v182
	v_med3_f32 v223, v223, 1.0, v182
	v_med3_f32 v224, v224, 1.0, v182
	v_med3_f32 v225, v225, 1.0, v182
	v_cvt_u32_f32_e32 v210, v210
	v_cvt_u32_f32_e32 v211, v211
	v_cvt_u32_f32_sdwa v212, v212 dst_sel:WORD_1 dst_unused:UNUSED_PAD src0_sel:DWORD
	v_cvt_u32_f32_sdwa v213, v213 dst_sel:BYTE_3 dst_unused:UNUSED_PAD src0_sel:DWORD
	v_cvt_u32_f32_e32 v214, v214
	v_cvt_u32_f32_e32 v215, v215
	v_cvt_u32_f32_sdwa v216, v216 dst_sel:WORD_1 dst_unused:UNUSED_PAD src0_sel:DWORD
	v_cvt_u32_f32_sdwa v217, v217 dst_sel:BYTE_3 dst_unused:UNUSED_PAD src0_sel:DWORD
	v_cvt_u32_f32_e32 v218, v218
	v_cvt_u32_f32_e32 v219, v219
	v_cvt_u32_f32_sdwa v220, v220 dst_sel:WORD_1 dst_unused:UNUSED_PAD src0_sel:DWORD
	v_cvt_u32_f32_sdwa v221, v221 dst_sel:BYTE_3 dst_unused:UNUSED_PAD src0_sel:DWORD
	v_cvt_u32_f32_e32 v222, v222
	v_cvt_u32_f32_e32 v223, v223
	v_cvt_u32_f32_sdwa v224, v224 dst_sel:WORD_1 dst_unused:UNUSED_PAD src0_sel:DWORD
	v_cvt_u32_f32_sdwa v225, v225 dst_sel:BYTE_3 dst_unused:UNUSED_PAD src0_sel:DWORD
	v_lshl_or_b32 v210, v211, 8, v210
	v_lshl_or_b32 v214, v215, 8, v214
	v_lshl_or_b32 v218, v219, 8, v218
	v_lshl_or_b32 v222, v223, 8, v222
	v_or3_b32 v236, v210, v212, v213
	v_or3_b32 v237, v214, v216, v217
	v_or3_b32 v238, v218, v220, v221
	v_or3_b32 v239, v222, v224, v225
	v_add_co_u32_e32 v146, vcc, 0x50000, v148
	s_nop 1
	v_addc_co_u32_e32 v147, vcc, 0, v149, vcc
	global_store_dwordx4 v[146:147], v[236:239], off nt
	s_waitcnt vmcnt(7)
	v_mul_f32_e32 v130, 0xbfb8aa3b, v209
	v_fma_f32 v210, v12, v130, v186
	v_fma_f32 v211, v13, v130, v187
	v_fma_f32 v212, v14, v130, v188
	v_fma_f32 v213, v15, v130, v189
	v_fma_f32 v214, v8, v130, v190
	v_fma_f32 v215, v9, v130, v191
	v_fma_f32 v216, v10, v130, v192
	v_fma_f32 v217, v11, v130, v193
	v_fma_f32 v218, v4, v130, v194
	v_fma_f32 v219, v5, v130, v195
	v_fma_f32 v220, v6, v130, v196
	v_fma_f32 v221, v7, v130, v197
	v_fma_f32 v222, v0, v130, v198
	v_fma_f32 v223, v1, v130, v199
	v_fma_f32 v224, v2, v130, v200
	v_fma_f32 v225, v3, v130, v201
	v_exp_f32_e32 v210, v210
	v_exp_f32_e32 v211, v211
	v_exp_f32_e32 v212, v212
	v_exp_f32_e32 v213, v213
	v_exp_f32_e32 v214, v214
	v_exp_f32_e32 v215, v215
	v_exp_f32_e32 v216, v216
	v_exp_f32_e32 v217, v217
	v_exp_f32_e32 v218, v218
	v_exp_f32_e32 v219, v219
	v_exp_f32_e32 v220, v220
	v_exp_f32_e32 v221, v221
	v_exp_f32_e32 v222, v222
	v_exp_f32_e32 v223, v223
	v_exp_f32_e32 v224, v224
	v_exp_f32_e32 v225, v225
	v_add_f32_e32 v210, 1.0, v210
	v_add_f32_e32 v211, 1.0, v211
	v_add_f32_e32 v212, 1.0, v212
	v_add_f32_e32 v213, 1.0, v213
	v_add_f32_e32 v214, 1.0, v214
	v_add_f32_e32 v215, 1.0, v215
	v_add_f32_e32 v216, 1.0, v216
	v_add_f32_e32 v217, 1.0, v217
	v_add_f32_e32 v218, 1.0, v218
	v_add_f32_e32 v219, 1.0, v219
	v_add_f32_e32 v220, 1.0, v220
	v_add_f32_e32 v221, 1.0, v221
	v_add_f32_e32 v222, 1.0, v222
	v_add_f32_e32 v223, 1.0, v223
	v_add_f32_e32 v224, 1.0, v224
	v_add_f32_e32 v225, 1.0, v225
	v_rcp_f32_e32 v210, v210
	v_rcp_f32_e32 v211, v211
	v_rcp_f32_e32 v212, v212
	v_rcp_f32_e32 v213, v213
	v_rcp_f32_e32 v214, v214
	v_rcp_f32_e32 v215, v215
	v_rcp_f32_e32 v216, v216
	v_rcp_f32_e32 v217, v217
	v_rcp_f32_e32 v218, v218
	v_rcp_f32_e32 v219, v219
	v_rcp_f32_e32 v220, v220
	v_rcp_f32_e32 v221, v221
	v_rcp_f32_e32 v222, v222
	v_rcp_f32_e32 v223, v223
	v_rcp_f32_e32 v224, v224
	v_rcp_f32_e32 v225, v225
	v_fma_f32 v210, v210, s84, 0.5
	v_fma_f32 v211, v211, s84, 0.5
	v_fma_f32 v212, v212, s84, 0.5
	v_fma_f32 v213, v213, s84, 0.5
	v_fma_f32 v214, v214, s84, 0.5
	v_fma_f32 v215, v215, s84, 0.5
	v_fma_f32 v216, v216, s84, 0.5
	v_fma_f32 v217, v217, s84, 0.5
	v_fma_f32 v218, v218, s84, 0.5
	v_fma_f32 v219, v219, s84, 0.5
	v_fma_f32 v220, v220, s84, 0.5
	v_fma_f32 v221, v221, s84, 0.5
	v_fma_f32 v222, v222, s84, 0.5
	v_fma_f32 v223, v223, s84, 0.5
	v_fma_f32 v224, v224, s84, 0.5
	v_fma_f32 v225, v225, s84, 0.5
	v_med3_f32 v210, v210, 1.0, v182
	v_med3_f32 v211, v211, 1.0, v182
	v_med3_f32 v212, v212, 1.0, v182
	v_med3_f32 v213, v213, 1.0, v182
	v_med3_f32 v214, v214, 1.0, v182
	v_med3_f32 v215, v215, 1.0, v182
	v_med3_f32 v216, v216, 1.0, v182
	v_med3_f32 v217, v217, 1.0, v182
	v_med3_f32 v218, v218, 1.0, v182
	v_med3_f32 v219, v219, 1.0, v182
	v_med3_f32 v220, v220, 1.0, v182
	v_med3_f32 v221, v221, 1.0, v182
	v_med3_f32 v222, v222, 1.0, v182
	v_med3_f32 v223, v223, 1.0, v182
	v_med3_f32 v224, v224, 1.0, v182
	v_med3_f32 v225, v225, 1.0, v182
	v_cvt_u32_f32_e32 v210, v210
	v_cvt_u32_f32_e32 v211, v211
	v_cvt_u32_f32_sdwa v212, v212 dst_sel:WORD_1 dst_unused:UNUSED_PAD src0_sel:DWORD
	v_cvt_u32_f32_sdwa v213, v213 dst_sel:BYTE_3 dst_unused:UNUSED_PAD src0_sel:DWORD
	v_cvt_u32_f32_e32 v214, v214
	v_cvt_u32_f32_e32 v215, v215
	v_cvt_u32_f32_sdwa v216, v216 dst_sel:WORD_1 dst_unused:UNUSED_PAD src0_sel:DWORD
	v_cvt_u32_f32_sdwa v217, v217 dst_sel:BYTE_3 dst_unused:UNUSED_PAD src0_sel:DWORD
	v_cvt_u32_f32_e32 v218, v218
	v_cvt_u32_f32_e32 v219, v219
	v_cvt_u32_f32_sdwa v220, v220 dst_sel:WORD_1 dst_unused:UNUSED_PAD src0_sel:DWORD
	v_cvt_u32_f32_sdwa v221, v221 dst_sel:BYTE_3 dst_unused:UNUSED_PAD src0_sel:DWORD
	v_cvt_u32_f32_e32 v222, v222
	v_cvt_u32_f32_e32 v223, v223
	v_cvt_u32_f32_sdwa v224, v224 dst_sel:WORD_1 dst_unused:UNUSED_PAD src0_sel:DWORD
	v_cvt_u32_f32_sdwa v225, v225 dst_sel:BYTE_3 dst_unused:UNUSED_PAD src0_sel:DWORD
	v_lshl_or_b32 v210, v211, 8, v210
	v_lshl_or_b32 v214, v215, 8, v214
	v_lshl_or_b32 v218, v219, 8, v218
	v_lshl_or_b32 v222, v223, 8, v222
	v_or3_b32 v236, v210, v212, v213
	v_or3_b32 v237, v214, v216, v217
	v_or3_b32 v238, v218, v220, v221
	v_or3_b32 v239, v222, v224, v225
	v_add_co_u32_e32 v146, vcc, 0x58000, v148
	s_nop 1
	v_addc_co_u32_e32 v147, vcc, 0, v149, vcc
	global_store_dwordx4 v[146:147], v[236:239], off nt
	s_mov_b32 s12, 0x40000

.Lssm3_task:
	s_waitcnt vmcnt(2)
	v_mov_b32_e32 v100, v104
	v_mov_b32_e32 v101, v105
	v_mov_b32_e32 v102, v106
	v_mov_b32_e32 v103, v107
	v_mov_b32_e32 v112, v108
	v_mov_b32_e32 v113, v109
	v_mov_b32_e32 v114, v110
	v_mov_b32_e32 v115, v111
	v_mov_b32_e32 v116, v142
	v_mov_b32_e32 v117, v143
	v_add_u32_e32 v188, 0x400000, v188
	v_add_u32_e32 v191, 0x100000, v191
	v_add_u32_e32 v196, 0x8000, v188
	global_load_dwordx4 v[104:107], v188, s[6:7]
	global_load_dwordx4 v[108:111], v196, s[6:7]
	global_load_dword v142, v191, s[26:27]
	global_load_dword v143, v191, s[26:27] offset:256
	v_add_u32_e32 v197, 0x4000, v189
	v_add_u32_e32 v198, 0x8000, v189
	v_add_u32_e32 v199, 0xc000, v189
	global_load_ushort v124, v189, s[6:7]
	global_load_ushort v125, v189, s[6:7] offset:1024
	global_load_ushort v126, v189, s[6:7] offset:2048
	global_load_ushort v127, v189, s[6:7] offset:3072
	global_load_ushort v128, v197, s[6:7]
	global_load_ushort v129, v197, s[6:7] offset:1024
	global_load_ushort v130, v197, s[6:7] offset:2048
	global_load_ushort v131, v197, s[6:7] offset:3072
	global_load_ushort v132, v198, s[6:7]
	global_load_ushort v133, v198, s[6:7] offset:1024
	global_load_ushort v134, v198, s[6:7] offset:2048
	global_load_ushort v135, v198, s[6:7] offset:3072
	global_load_ushort v136, v199, s[6:7]
	global_load_ushort v137, v199, s[6:7] offset:1024
	global_load_ushort v138, v199, s[6:7] offset:2048
	global_load_ushort v139, v199, s[6:7] offset:3072
	v_mfma_f32_32x32x16_bf16 v[16:31], v[100:103], v[64:67], 0
	v_mfma_f32_32x32x16_bf16 v[32:47], v[100:103], v[68:71], 0
	v_mfma_f32_32x32x16_bf16 v[0:15], v[100:103], v[72:75], 0
	v_mfma_f32_32x32x16_bf16 v[48:63], v[100:103], v[76:79], 0
	s_nop 9
	v_permlane32_swap_b32_e32 v16, v32
	v_permlane32_swap_b32_e32 v17, v33
	v_permlane32_swap_b32_e32 v18, v34
	v_permlane32_swap_b32_e32 v19, v35
	v_permlane32_swap_b32_e32 v20, v36
	v_permlane32_swap_b32_e32 v21, v37
	v_permlane32_swap_b32_e32 v22, v38
	v_permlane32_swap_b32_e32 v23, v39
	v_permlane32_swap_b32_e32 v24, v40
	v_permlane32_swap_b32_e32 v25, v41
	v_permlane32_swap_b32_e32 v26, v42
	v_permlane32_swap_b32_e32 v27, v43
	v_permlane32_swap_b32_e32 v28, v44
	v_permlane32_swap_b32_e32 v29, v45
	v_permlane32_swap_b32_e32 v30, v46
	v_permlane32_swap_b32_e32 v31, v47
	v_permlane32_swap_b32_e32 v0, v48
	v_permlane32_swap_b32_e32 v1, v49
	v_permlane32_swap_b32_e32 v2, v50
	v_permlane32_swap_b32_e32 v3, v51
	v_permlane32_swap_b32_e32 v4, v52
	v_permlane32_swap_b32_e32 v5, v53
	v_permlane32_swap_b32_e32 v6, v54
	v_permlane32_swap_b32_e32 v7, v55
	v_permlane32_swap_b32_e32 v8, v56
	v_permlane32_swap_b32_e32 v9, v57
	v_permlane32_swap_b32_e32 v10, v58
	v_permlane32_swap_b32_e32 v11, v59
	v_permlane32_swap_b32_e32 v12, v60
	v_permlane32_swap_b32_e32 v13, v61
	v_permlane32_swap_b32_e32 v14, v62
	v_permlane32_swap_b32_e32 v15, v63
	v_fma_f32 v118, -v201, v117, v16
	v_fma_f32 v119, v201, v116, v0
	v_fma_f32 v116, v200, v116, v118
	v_fma_f32 v117, v200, v117, v119
	v_cvt_pk_bf16_f32 v120, v116, v117
	ds_write_b32 v192, v120
	v_fma_f32 v118, -v201, v117, v17
	v_fma_f32 v119, v201, v116, v1
	v_fma_f32 v116, v200, v116, v118
	v_fma_f32 v117, v200, v117, v119
	v_cvt_pk_bf16_f32 v121, v116, v117
	ds_write_b32 v192, v121 offset:272
	v_fma_f32 v118, -v201, v117, v18
	v_fma_f32 v119, v201, v116, v2
	v_fma_f32 v116, v200, v116, v118
	v_fma_f32 v117, v200, v117, v119
	v_cvt_pk_bf16_f32 v120, v116, v117
	ds_write_b32 v192, v120 offset:544
	v_fma_f32 v118, -v201, v117, v19
	v_fma_f32 v119, v201, v116, v3
	v_fma_f32 v116, v200, v116, v118
	v_fma_f32 v117, v200, v117, v119
	v_cvt_pk_bf16_f32 v121, v116, v117
	ds_write_b32 v192, v121 offset:816
	v_fma_f32 v118, -v201, v117, v32
	v_fma_f32 v119, v201, v116, v48
	v_fma_f32 v116, v200, v116, v118
	v_fma_f32 v117, v200, v117, v119
	v_cvt_pk_bf16_f32 v120, v116, v117
	ds_write_b32 v192, v120 offset:1088
	v_fma_f32 v118, -v201, v117, v33
	v_fma_f32 v119, v201, v116, v49
	v_fma_f32 v116, v200, v116, v118
	v_fma_f32 v117, v200, v117, v119
	v_cvt_pk_bf16_f32 v121, v116, v117
	ds_write_b32 v192, v121 offset:1360
	v_fma_f32 v118, -v201, v117, v34
	v_fma_f32 v119, v201, v116, v50
	v_fma_f32 v116, v200, v116, v118
	v_fma_f32 v117, v200, v117, v119
	v_cvt_pk_bf16_f32 v120, v116, v117
	ds_write_b32 v192, v120 offset:1632
	v_fma_f32 v118, -v201, v117, v35
	v_fma_f32 v119, v201, v116, v51
	v_fma_f32 v116, v200, v116, v118
	v_fma_f32 v117, v200, v117, v119
	v_cvt_pk_bf16_f32 v121, v116, v117
	ds_write_b32 v192, v121 offset:1904
	v_fma_f32 v118, -v201, v117, v20
	v_fma_f32 v119, v201, v116, v4
	v_fma_f32 v116, v200, v116, v118
	v_fma_f32 v117, v200, v117, v119
	v_cvt_pk_bf16_f32 v120, v116, v117
	ds_write_b32 v192, v120 offset:2176
	v_fma_f32 v118, -v201, v117, v21
	v_fma_f32 v119, v201, v116, v5
	v_fma_f32 v116, v200, v116, v118
	v_fma_f32 v117, v200, v117, v119
	v_cvt_pk_bf16_f32 v121, v116, v117
	ds_write_b32 v192, v121 offset:2448
	v_fma_f32 v118, -v201, v117, v22
	v_fma_f32 v119, v201, v116, v6
	v_fma_f32 v116, v200, v116, v118
	v_fma_f32 v117, v200, v117, v119
	v_cvt_pk_bf16_f32 v120, v116, v117
	ds_write_b32 v192, v120 offset:2720
	v_fma_f32 v118, -v201, v117, v23
	v_fma_f32 v119, v201, v116, v7
	v_fma_f32 v116, v200, v116, v118
	v_fma_f32 v117, v200, v117, v119
	v_cvt_pk_bf16_f32 v121, v116, v117
	ds_write_b32 v192, v121 offset:2992
	v_fma_f32 v118, -v201, v117, v36
	v_fma_f32 v119, v201, v116, v52
	v_fma_f32 v116, v200, v116, v118
	v_fma_f32 v117, v200, v117, v119
	v_cvt_pk_bf16_f32 v120, v116, v117
	ds_write_b32 v192, v120 offset:3264
	v_fma_f32 v118, -v201, v117, v37
	v_fma_f32 v119, v201, v116, v53
	v_fma_f32 v116, v200, v116, v118
	v_fma_f32 v117, v200, v117, v119
	v_cvt_pk_bf16_f32 v121, v116, v117
	ds_write_b32 v192, v121 offset:3536
	v_fma_f32 v118, -v201, v117, v38
	v_fma_f32 v119, v201, v116, v54
	v_fma_f32 v116, v200, v116, v118
	v_fma_f32 v117, v200, v117, v119
	v_cvt_pk_bf16_f32 v120, v116, v117
	ds_write_b32 v192, v120 offset:3808
	v_fma_f32 v118, -v201, v117, v39
	v_fma_f32 v119, v201, v116, v55
	v_fma_f32 v116, v200, v116, v118
	v_fma_f32 v117, v200, v117, v119
	v_cvt_pk_bf16_f32 v121, v116, v117
	ds_write_b32 v192, v121 offset:4080
	v_fma_f32 v118, -v201, v117, v24
	v_fma_f32 v119, v201, v116, v8
	v_fma_f32 v116, v200, v116, v118
	v_fma_f32 v117, v200, v117, v119
	v_cvt_pk_bf16_f32 v120, v116, v117
	ds_write_b32 v192, v120 offset:4352
	v_fma_f32 v118, -v201, v117, v25
	v_fma_f32 v119, v201, v116, v9
	v_fma_f32 v116, v200, v116, v118
	v_fma_f32 v117, v200, v117, v119
	v_cvt_pk_bf16_f32 v121, v116, v117
	ds_write_b32 v192, v121 offset:4624
	v_fma_f32 v118, -v201, v117, v26
	v_fma_f32 v119, v201, v116, v10
	v_fma_f32 v116, v200, v116, v118
	v_fma_f32 v117, v200, v117, v119
	v_cvt_pk_bf16_f32 v120, v116, v117
	ds_write_b32 v192, v120 offset:4896
	v_fma_f32 v118, -v201, v117, v27
	v_fma_f32 v119, v201, v116, v11
	v_fma_f32 v116, v200, v116, v118
	v_fma_f32 v117, v200, v117, v119
	v_cvt_pk_bf16_f32 v121, v116, v117
	ds_write_b32 v192, v121 offset:5168
	v_fma_f32 v118, -v201, v117, v40
	v_fma_f32 v119, v201, v116, v56
	v_fma_f32 v116, v200, v116, v118
	v_fma_f32 v117, v200, v117, v119
	v_cvt_pk_bf16_f32 v120, v116, v117
	ds_write_b32 v192, v120 offset:5440
	v_fma_f32 v118, -v201, v117, v41
	v_fma_f32 v119, v201, v116, v57
	v_fma_f32 v116, v200, v116, v118
	v_fma_f32 v117, v200, v117, v119
	v_cvt_pk_bf16_f32 v121, v116, v117
	ds_write_b32 v192, v121 offset:5712
	v_fma_f32 v118, -v201, v117, v42
	v_fma_f32 v119, v201, v116, v58
	v_fma_f32 v116, v200, v116, v118
	v_fma_f32 v117, v200, v117, v119
	v_cvt_pk_bf16_f32 v120, v116, v117
	ds_write_b32 v192, v120 offset:5984
	v_fma_f32 v118, -v201, v117, v43
	v_fma_f32 v119, v201, v116, v59
	v_fma_f32 v116, v200, v116, v118
	v_fma_f32 v117, v200, v117, v119
	v_cvt_pk_bf16_f32 v121, v116, v117
	ds_write_b32 v192, v121 offset:6256
	v_fma_f32 v118, -v201, v117, v28
	v_fma_f32 v119, v201, v116, v12
	v_fma_f32 v116, v200, v116, v118
	v_fma_f32 v117, v200, v117, v119
	v_cvt_pk_bf16_f32 v120, v116, v117
	ds_write_b32 v192, v120 offset:6528
	v_fma_f32 v118, -v201, v117, v29
	v_fma_f32 v119, v201, v116, v13
	v_fma_f32 v116, v200, v116, v118
	v_fma_f32 v117, v200, v117, v119
	v_cvt_pk_bf16_f32 v121, v116, v117
	ds_write_b32 v192, v121 offset:6800
	v_fma_f32 v118, -v201, v117, v30
	v_fma_f32 v119, v201, v116, v14
	v_fma_f32 v116, v200, v116, v118
	v_fma_f32 v117, v200, v117, v119
	v_cvt_pk_bf16_f32 v120, v116, v117
	ds_write_b32 v192, v120 offset:7072
	v_fma_f32 v118, -v201, v117, v31
	v_fma_f32 v119, v201, v116, v15
	v_fma_f32 v116, v200, v116, v118
	v_fma_f32 v117, v200, v117, v119
	v_cvt_pk_bf16_f32 v121, v116, v117
	ds_write_b32 v192, v121 offset:7344
	v_fma_f32 v118, -v201, v117, v44
	v_fma_f32 v119, v201, v116, v60
	v_fma_f32 v116, v200, v116, v118
	v_fma_f32 v117, v200, v117, v119
	v_cvt_pk_bf16_f32 v120, v116, v117
	ds_write_b32 v192, v120 offset:7616
	v_fma_f32 v118, -v201, v117, v45
	v_fma_f32 v119, v201, v116, v61
	v_fma_f32 v116, v200, v116, v118
	v_fma_f32 v117, v200, v117, v119
	v_cvt_pk_bf16_f32 v121, v116, v117
	ds_write_b32 v192, v121 offset:7888
	v_fma_f32 v118, -v201, v117, v46
	v_fma_f32 v119, v201, v116, v62
	v_fma_f32 v116, v200, v116, v118
	v_fma_f32 v117, v200, v117, v119
	v_cvt_pk_bf16_f32 v120, v116, v117
	ds_write_b32 v192, v120 offset:8160
	v_fma_f32 v118, -v201, v117, v47
	v_fma_f32 v119, v201, v116, v63
	v_fma_f32 v116, v200, v116, v118
	v_fma_f32 v117, v200, v117, v119
	v_cvt_pk_bf16_f32 v121, v116, v117
	ds_write_b32 v192, v121 offset:8432
	ds_read_b128 v[210:213], v193
	ds_read_b128 v[214:217], v193 offset:64
	ds_read_b128 v[218:221], v193 offset:128
	ds_read_b128 v[222:225], v193 offset:192
	ds_read_b128 v[226:229], v193 offset:4352
	ds_read_b128 v[230:233], v193 offset:4416
	ds_read_b128 v[234:237], v193 offset:4480
	ds_read_b128 v[238:241], v193 offset:4544
	s_waitcnt lgkmcnt(7)
	v_mfma_f32_16x16x32_bf16 v[176:179], v[210:213], v[80:83], 0
	s_waitcnt lgkmcnt(6)
	v_mfma_f32_16x16x32_bf16 v[176:179], v[214:217], v[84:87], v[176:179]
	s_waitcnt lgkmcnt(5)
	v_mfma_f32_16x16x32_bf16 v[176:179], v[218:221], v[88:91], v[176:179]
	s_waitcnt lgkmcnt(4)
	v_mfma_f32_16x16x32_bf16 v[176:179], v[222:225], v[92:95], v[176:179]
	s_waitcnt lgkmcnt(3)
	v_mfma_f32_16x16x32_bf16 v[180:183], v[226:229], v[80:83], 0
	s_waitcnt lgkmcnt(2)
	v_mfma_f32_16x16x32_bf16 v[180:183], v[230:233], v[84:87], v[180:183]
	s_waitcnt lgkmcnt(1)
	v_mfma_f32_16x16x32_bf16 v[180:183], v[234:237], v[88:91], v[180:183]
	s_waitcnt lgkmcnt(0)
	v_mfma_f32_16x16x32_bf16 v[180:183], v[238:241], v[92:95], v[180:183]
	s_waitcnt vmcnt(8)
	v_lshlrev_b32_e32 v145, 16, v124
	v_lshlrev_b32_e32 v149, 16, v125
	v_lshlrev_b32_e32 v153, 16, v126
	v_lshlrev_b32_e32 v157, 16, v127
	v_fma_f32 v144, v202, v145, v176
	v_fma_f32 v148, v202, v149, v177
	v_fma_f32 v152, v202, v153, v178
	v_fma_f32 v156, v202, v157, v179
	v_mul_f32_e32 v145, 0x3d372713, v144
	v_mul_f32_e32 v149, 0x3d372713, v148
	v_mul_f32_e32 v153, 0x3d372713, v152
	v_mul_f32_e32 v157, 0x3d372713, v156
	v_mul_f32_e32 v145, v145, v144
	v_mul_f32_e32 v149, v149, v148
	v_mul_f32_e32 v153, v153, v152
	v_mul_f32_e32 v157, v157, v156
	v_fma_f32 v146, v145, v144, v144
	v_fma_f32 v150, v149, v148, v148
	v_fma_f32 v154, v153, v152, v152
	v_fma_f32 v158, v157, v156, v156
	v_mul_f32_e32 v146, 0xc0135761, v146
	v_mul_f32_e32 v150, 0xc0135761, v150
	v_mul_f32_e32 v154, 0xc0135761, v154
	v_mul_f32_e32 v158, 0xc0135761, v158
	v_exp_f32_e32 v147, v146
	v_exp_f32_e32 v151, v150
	v_exp_f32_e32 v155, v154
	v_exp_f32_e32 v159, v158
	v_add_f32_e32 v147, 1.0, v147
	v_add_f32_e32 v151, 1.0, v151
	v_add_f32_e32 v155, 1.0, v155
	v_add_f32_e32 v159, 1.0, v159
	v_rcp_f32_e32 v147, v147
	v_rcp_f32_e32 v151, v151
	v_rcp_f32_e32 v155, v155
	v_rcp_f32_e32 v159, v159
	v_mul_f32_e32 v144, v144, v147
	v_mul_f32_e32 v148, v148, v151
	v_mul_f32_e32 v152, v152, v155
	v_mul_f32_e32 v156, v156, v159
	v_cvt_pk_bf16_f32 v145, v144, v144
	v_cvt_pk_bf16_f32 v149, v148, v148
	v_cvt_pk_bf16_f32 v153, v152, v152
	v_cvt_pk_bf16_f32 v157, v156, v156
	ds_write_b16 v194, v145
	ds_write_b16 v194, v149 offset:32
	ds_write_b16 v194, v153 offset:64
	ds_write_b16 v194, v157 offset:96
	v_lshlrev_b32_e32 v145, 16, v128
	v_lshlrev_b32_e32 v149, 16, v129
	v_lshlrev_b32_e32 v153, 16, v130
	v_lshlrev_b32_e32 v157, 16, v131
	v_fma_f32 v144, v202, v145, v180
	v_fma_f32 v148, v202, v149, v181
	v_fma_f32 v152, v202, v153, v182
	v_fma_f32 v156, v202, v157, v183
	v_mul_f32_e32 v145, 0x3d372713, v144
	v_mul_f32_e32 v149, 0x3d372713, v148
	v_mul_f32_e32 v153, 0x3d372713, v152
	v_mul_f32_e32 v157, 0x3d372713, v156
	v_mul_f32_e32 v145, v145, v144
	v_mul_f32_e32 v149, v149, v148
	v_mul_f32_e32 v153, v153, v152
	v_mul_f32_e32 v157, v157, v156
	v_fma_f32 v146, v145, v144, v144
	v_fma_f32 v150, v149, v148, v148
	v_fma_f32 v154, v153, v152, v152
	v_fma_f32 v158, v157, v156, v156
	v_mul_f32_e32 v146, 0xc0135761, v146
	v_mul_f32_e32 v150, 0xc0135761, v150
	v_mul_f32_e32 v154, 0xc0135761, v154
	v_mul_f32_e32 v158, 0xc0135761, v158
	v_exp_f32_e32 v147, v146
	v_exp_f32_e32 v151, v150
	v_exp_f32_e32 v155, v154
	v_exp_f32_e32 v159, v158
	v_add_f32_e32 v147, 1.0, v147
	v_add_f32_e32 v151, 1.0, v151
	v_add_f32_e32 v155, 1.0, v155
	v_add_f32_e32 v159, 1.0, v159
	v_rcp_f32_e32 v147, v147
	v_rcp_f32_e32 v151, v151
	v_rcp_f32_e32 v155, v155
	v_rcp_f32_e32 v159, v159
	v_mul_f32_e32 v144, v144, v147
	v_mul_f32_e32 v148, v148, v151
	v_mul_f32_e32 v152, v152, v155
	v_mul_f32_e32 v156, v156, v159
	v_cvt_pk_bf16_f32 v145, v144, v144
	v_cvt_pk_bf16_f32 v149, v148, v148
	v_cvt_pk_bf16_f32 v153, v152, v152
	v_cvt_pk_bf16_f32 v157, v156, v156
	ds_write_b16 v194, v145 offset:512
	ds_write_b16 v194, v149 offset:544
	ds_write_b16 v194, v153 offset:576
	ds_write_b16 v194, v157 offset:608
	ds_read_b128 v[184:187], v195
	s_waitcnt lgkmcnt(0)
	global_store_dwordx4 v190, v[184:187], s[6:7]
	v_mfma_f32_32x32x16_bf16 v[16:31], v[112:115], v[64:67], 0
	v_mfma_f32_32x32x16_bf16 v[32:47], v[112:115], v[68:71], 0
	v_mfma_f32_32x32x16_bf16 v[0:15], v[112:115], v[72:75], 0
	v_mfma_f32_32x32x16_bf16 v[48:63], v[112:115], v[76:79], 0
	s_nop 9
	v_permlane32_swap_b32_e32 v16, v32
	v_permlane32_swap_b32_e32 v17, v33
	v_permlane32_swap_b32_e32 v18, v34
	v_permlane32_swap_b32_e32 v19, v35
	v_permlane32_swap_b32_e32 v20, v36
	v_permlane32_swap_b32_e32 v21, v37
	v_permlane32_swap_b32_e32 v22, v38
	v_permlane32_swap_b32_e32 v23, v39
	v_permlane32_swap_b32_e32 v24, v40
	v_permlane32_swap_b32_e32 v25, v41
	v_permlane32_swap_b32_e32 v26, v42
	v_permlane32_swap_b32_e32 v27, v43
	v_permlane32_swap_b32_e32 v28, v44
	v_permlane32_swap_b32_e32 v29, v45
	v_permlane32_swap_b32_e32 v30, v46
	v_permlane32_swap_b32_e32 v31, v47
	v_permlane32_swap_b32_e32 v0, v48
	v_permlane32_swap_b32_e32 v1, v49
	v_permlane32_swap_b32_e32 v2, v50
	v_permlane32_swap_b32_e32 v3, v51
	v_permlane32_swap_b32_e32 v4, v52
	v_permlane32_swap_b32_e32 v5, v53
	v_permlane32_swap_b32_e32 v6, v54
	v_permlane32_swap_b32_e32 v7, v55
	v_permlane32_swap_b32_e32 v8, v56
	v_permlane32_swap_b32_e32 v9, v57
	v_permlane32_swap_b32_e32 v10, v58
	v_permlane32_swap_b32_e32 v11, v59
	v_permlane32_swap_b32_e32 v12, v60
	v_permlane32_swap_b32_e32 v13, v61
	v_permlane32_swap_b32_e32 v14, v62
	v_permlane32_swap_b32_e32 v15, v63
	v_fma_f32 v118, -v201, v117, v16
	v_fma_f32 v119, v201, v116, v0
	v_fma_f32 v116, v200, v116, v118
	v_fma_f32 v117, v200, v117, v119
	v_cvt_pk_bf16_f32 v120, v116, v117
	ds_write_b32 v192, v120
	v_fma_f32 v118, -v201, v117, v17
	v_fma_f32 v119, v201, v116, v1
	v_fma_f32 v116, v200, v116, v118
	v_fma_f32 v117, v200, v117, v119
	v_cvt_pk_bf16_f32 v121, v116, v117
	ds_write_b32 v192, v121 offset:272
	v_fma_f32 v118, -v201, v117, v18
	v_fma_f32 v119, v201, v116, v2
	v_fma_f32 v116, v200, v116, v118
	v_fma_f32 v117, v200, v117, v119
	v_cvt_pk_bf16_f32 v120, v116, v117
	ds_write_b32 v192, v120 offset:544
	v_fma_f32 v118, -v201, v117, v19
	v_fma_f32 v119, v201, v116, v3
	v_fma_f32 v116, v200, v116, v118
	v_fma_f32 v117, v200, v117, v119
	v_cvt_pk_bf16_f32 v121, v116, v117
	ds_write_b32 v192, v121 offset:816
	v_fma_f32 v118, -v201, v117, v32
	v_fma_f32 v119, v201, v116, v48
	v_fma_f32 v116, v200, v116, v118
	v_fma_f32 v117, v200, v117, v119
	v_cvt_pk_bf16_f32 v120, v116, v117
	ds_write_b32 v192, v120 offset:1088
	v_fma_f32 v118, -v201, v117, v33
	v_fma_f32 v119, v201, v116, v49
	v_fma_f32 v116, v200, v116, v118
	v_fma_f32 v117, v200, v117, v119
	v_cvt_pk_bf16_f32 v121, v116, v117
	ds_write_b32 v192, v121 offset:1360
	v_fma_f32 v118, -v201, v117, v34
	v_fma_f32 v119, v201, v116, v50
	v_fma_f32 v116, v200, v116, v118
	v_fma_f32 v117, v200, v117, v119
	v_cvt_pk_bf16_f32 v120, v116, v117
	ds_write_b32 v192, v120 offset:1632
	v_fma_f32 v118, -v201, v117, v35
	v_fma_f32 v119, v201, v116, v51
	v_fma_f32 v116, v200, v116, v118
	v_fma_f32 v117, v200, v117, v119
	v_cvt_pk_bf16_f32 v121, v116, v117
	ds_write_b32 v192, v121 offset:1904
	v_fma_f32 v118, -v201, v117, v20
	v_fma_f32 v119, v201, v116, v4
	v_fma_f32 v116, v200, v116, v118
	v_fma_f32 v117, v200, v117, v119
	v_cvt_pk_bf16_f32 v120, v116, v117
	ds_write_b32 v192, v120 offset:2176
	v_fma_f32 v118, -v201, v117, v21
	v_fma_f32 v119, v201, v116, v5
	v_fma_f32 v116, v200, v116, v118
	v_fma_f32 v117, v200, v117, v119
	v_cvt_pk_bf16_f32 v121, v116, v117
	ds_write_b32 v192, v121 offset:2448
	v_fma_f32 v118, -v201, v117, v22
	v_fma_f32 v119, v201, v116, v6
	v_fma_f32 v116, v200, v116, v118
	v_fma_f32 v117, v200, v117, v119
	v_cvt_pk_bf16_f32 v120, v116, v117
	ds_write_b32 v192, v120 offset:2720
	v_fma_f32 v118, -v201, v117, v23
	v_fma_f32 v119, v201, v116, v7
	v_fma_f32 v116, v200, v116, v118
	v_fma_f32 v117, v200, v117, v119
	v_cvt_pk_bf16_f32 v121, v116, v117
	ds_write_b32 v192, v121 offset:2992
	v_fma_f32 v118, -v201, v117, v36
	v_fma_f32 v119, v201, v116, v52
	v_fma_f32 v116, v200, v116, v118
	v_fma_f32 v117, v200, v117, v119
	v_cvt_pk_bf16_f32 v120, v116, v117
	ds_write_b32 v192, v120 offset:3264
	v_fma_f32 v118, -v201, v117, v37
	v_fma_f32 v119, v201, v116, v53
	v_fma_f32 v116, v200, v116, v118
	v_fma_f32 v117, v200, v117, v119
	v_cvt_pk_bf16_f32 v121, v116, v117
	ds_write_b32 v192, v121 offset:3536
	v_fma_f32 v118, -v201, v117, v38
	v_fma_f32 v119, v201, v116, v54
	v_fma_f32 v116, v200, v116, v118
	v_fma_f32 v117, v200, v117, v119
	v_cvt_pk_bf16_f32 v120, v116, v117
	ds_write_b32 v192, v120 offset:3808
	v_fma_f32 v118, -v201, v117, v39
	v_fma_f32 v119, v201, v116, v55
	v_fma_f32 v116, v200, v116, v118
	v_fma_f32 v117, v200, v117, v119
	v_cvt_pk_bf16_f32 v121, v116, v117
	ds_write_b32 v192, v121 offset:4080
	v_fma_f32 v118, -v201, v117, v24
	v_fma_f32 v119, v201, v116, v8
	v_fma_f32 v116, v200, v116, v118
	v_fma_f32 v117, v200, v117, v119
	v_cvt_pk_bf16_f32 v120, v116, v117
	ds_write_b32 v192, v120 offset:4352
	v_fma_f32 v118, -v201, v117, v25
	v_fma_f32 v119, v201, v116, v9
	v_fma_f32 v116, v200, v116, v118
	v_fma_f32 v117, v200, v117, v119
	v_cvt_pk_bf16_f32 v121, v116, v117
	ds_write_b32 v192, v121 offset:4624
	v_fma_f32 v118, -v201, v117, v26
	v_fma_f32 v119, v201, v116, v10
	v_fma_f32 v116, v200, v116, v118
	v_fma_f32 v117, v200, v117, v119
	v_cvt_pk_bf16_f32 v120, v116, v117
	ds_write_b32 v192, v120 offset:4896
	v_fma_f32 v118, -v201, v117, v27
	v_fma_f32 v119, v201, v116, v11
	v_fma_f32 v116, v200, v116, v118
	v_fma_f32 v117, v200, v117, v119
	v_cvt_pk_bf16_f32 v121, v116, v117
	ds_write_b32 v192, v121 offset:5168
	v_fma_f32 v118, -v201, v117, v40
	v_fma_f32 v119, v201, v116, v56
	v_fma_f32 v116, v200, v116, v118
	v_fma_f32 v117, v200, v117, v119
	v_cvt_pk_bf16_f32 v120, v116, v117
	ds_write_b32 v192, v120 offset:5440
	v_fma_f32 v118, -v201, v117, v41
	v_fma_f32 v119, v201, v116, v57
	v_fma_f32 v116, v200, v116, v118
	v_fma_f32 v117, v200, v117, v119
	v_cvt_pk_bf16_f32 v121, v116, v117
	ds_write_b32 v192, v121 offset:5712
	v_fma_f32 v118, -v201, v117, v42
	v_fma_f32 v119, v201, v116, v58
	v_fma_f32 v116, v200, v116, v118
	v_fma_f32 v117, v200, v117, v119
	v_cvt_pk_bf16_f32 v120, v116, v117
	ds_write_b32 v192, v120 offset:5984
	v_fma_f32 v118, -v201, v117, v43
	v_fma_f32 v119, v201, v116, v59
	v_fma_f32 v116, v200, v116, v118
	v_fma_f32 v117, v200, v117, v119
	v_cvt_pk_bf16_f32 v121, v116, v117
	ds_write_b32 v192, v121 offset:6256
	v_fma_f32 v118, -v201, v117, v28
	v_fma_f32 v119, v201, v116, v12
	v_fma_f32 v116, v200, v116, v118
	v_fma_f32 v117, v200, v117, v119
	v_cvt_pk_bf16_f32 v120, v116, v117
	ds_write_b32 v192, v120 offset:6528
	v_fma_f32 v118, -v201, v117, v29
	v_fma_f32 v119, v201, v116, v13
	v_fma_f32 v116, v200, v116, v118
	v_fma_f32 v117, v200, v117, v119
	v_cvt_pk_bf16_f32 v121, v116, v117
	ds_write_b32 v192, v121 offset:6800
	v_fma_f32 v118, -v201, v117, v30
	v_fma_f32 v119, v201, v116, v14
	v_fma_f32 v116, v200, v116, v118
	v_fma_f32 v117, v200, v117, v119
	v_cvt_pk_bf16_f32 v120, v116, v117
	ds_write_b32 v192, v120 offset:7072
	v_fma_f32 v118, -v201, v117, v31
	v_fma_f32 v119, v201, v116, v15
	v_fma_f32 v116, v200, v116, v118
	v_fma_f32 v117, v200, v117, v119
	v_cvt_pk_bf16_f32 v121, v116, v117
	ds_write_b32 v192, v121 offset:7344
	v_fma_f32 v118, -v201, v117, v44
	v_fma_f32 v119, v201, v116, v60
	v_fma_f32 v116, v200, v116, v118
	v_fma_f32 v117, v200, v117, v119
	v_cvt_pk_bf16_f32 v120, v116, v117
	ds_write_b32 v192, v120 offset:7616
	v_fma_f32 v118, -v201, v117, v45
	v_fma_f32 v119, v201, v116, v61
	v_fma_f32 v116, v200, v116, v118
	v_fma_f32 v117, v200, v117, v119
	v_cvt_pk_bf16_f32 v121, v116, v117
	ds_write_b32 v192, v121 offset:7888
	v_fma_f32 v118, -v201, v117, v46
	v_fma_f32 v119, v201, v116, v62
	v_fma_f32 v116, v200, v116, v118
	v_fma_f32 v117, v200, v117, v119
	v_cvt_pk_bf16_f32 v120, v116, v117
	ds_write_b32 v192, v120 offset:8160
	v_fma_f32 v118, -v201, v117, v47
	v_fma_f32 v119, v201, v116, v63
	v_fma_f32 v116, v200, v116, v118
	v_fma_f32 v117, v200, v117, v119
	v_cvt_pk_bf16_f32 v121, v116, v117
	ds_write_b32 v192, v121 offset:8432
	ds_read_b128 v[210:213], v193
	ds_read_b128 v[214:217], v193 offset:64
	ds_read_b128 v[218:221], v193 offset:128
	ds_read_b128 v[222:225], v193 offset:192
	ds_read_b128 v[226:229], v193 offset:4352
	ds_read_b128 v[230:233], v193 offset:4416
	ds_read_b128 v[234:237], v193 offset:4480
	ds_read_b128 v[238:241], v193 offset:4544
	s_waitcnt lgkmcnt(7)
	v_mfma_f32_16x16x32_bf16 v[176:179], v[210:213], v[80:83], 0
	s_waitcnt lgkmcnt(6)
	v_mfma_f32_16x16x32_bf16 v[176:179], v[214:217], v[84:87], v[176:179]
	s_waitcnt lgkmcnt(5)
	v_mfma_f32_16x16x32_bf16 v[176:179], v[218:221], v[88:91], v[176:179]
	s_waitcnt lgkmcnt(4)
	v_mfma_f32_16x16x32_bf16 v[176:179], v[222:225], v[92:95], v[176:179]
	s_waitcnt lgkmcnt(3)
	v_mfma_f32_16x16x32_bf16 v[180:183], v[226:229], v[80:83], 0
	s_waitcnt lgkmcnt(2)
	v_mfma_f32_16x16x32_bf16 v[180:183], v[230:233], v[84:87], v[180:183]
	s_waitcnt lgkmcnt(1)
	v_mfma_f32_16x16x32_bf16 v[180:183], v[234:237], v[88:91], v[180:183]
	s_waitcnt lgkmcnt(0)
	v_mfma_f32_16x16x32_bf16 v[180:183], v[238:241], v[92:95], v[180:183]
	s_waitcnt vmcnt(1)
	v_lshlrev_b32_e32 v145, 16, v132
	v_lshlrev_b32_e32 v149, 16, v133
	v_lshlrev_b32_e32 v153, 16, v134
	v_lshlrev_b32_e32 v157, 16, v135
	v_fma_f32 v144, v202, v145, v176
	v_fma_f32 v148, v202, v149, v177
	v_fma_f32 v152, v202, v153, v178
	v_fma_f32 v156, v202, v157, v179
	v_mul_f32_e32 v145, 0x3d372713, v144
	v_mul_f32_e32 v149, 0x3d372713, v148
	v_mul_f32_e32 v153, 0x3d372713, v152
	v_mul_f32_e32 v157, 0x3d372713, v156
	v_mul_f32_e32 v145, v145, v144
	v_mul_f32_e32 v149, v149, v148
	v_mul_f32_e32 v153, v153, v152
	v_mul_f32_e32 v157, v157, v156
	v_fma_f32 v146, v145, v144, v144
	v_fma_f32 v150, v149, v148, v148
	v_fma_f32 v154, v153, v152, v152
	v_fma_f32 v158, v157, v156, v156
	v_mul_f32_e32 v146, 0xc0135761, v146
	v_mul_f32_e32 v150, 0xc0135761, v150
	v_mul_f32_e32 v154, 0xc0135761, v154
	v_mul_f32_e32 v158, 0xc0135761, v158
	v_exp_f32_e32 v147, v146
	v_exp_f32_e32 v151, v150
	v_exp_f32_e32 v155, v154
	v_exp_f32_e32 v159, v158
	v_add_f32_e32 v147, 1.0, v147
	v_add_f32_e32 v151, 1.0, v151
	v_add_f32_e32 v155, 1.0, v155
	v_add_f32_e32 v159, 1.0, v159
	v_rcp_f32_e32 v147, v147
	v_rcp_f32_e32 v151, v151
	v_rcp_f32_e32 v155, v155
	v_rcp_f32_e32 v159, v159
	v_mul_f32_e32 v144, v144, v147
	v_mul_f32_e32 v148, v148, v151
	v_mul_f32_e32 v152, v152, v155
	v_mul_f32_e32 v156, v156, v159
	v_cvt_pk_bf16_f32 v145, v144, v144
	v_cvt_pk_bf16_f32 v149, v148, v148
	v_cvt_pk_bf16_f32 v153, v152, v152
	v_cvt_pk_bf16_f32 v157, v156, v156
	ds_write_b16 v194, v145
	ds_write_b16 v194, v149 offset:32
	ds_write_b16 v194, v153 offset:64
	ds_write_b16 v194, v157 offset:96
	v_lshlrev_b32_e32 v145, 16, v136
	v_lshlrev_b32_e32 v149, 16, v137
	v_lshlrev_b32_e32 v153, 16, v138
	v_lshlrev_b32_e32 v157, 16, v139
	v_fma_f32 v144, v202, v145, v180
	v_fma_f32 v148, v202, v149, v181
	v_fma_f32 v152, v202, v153, v182
	v_fma_f32 v156, v202, v157, v183
	v_mul_f32_e32 v145, 0x3d372713, v144
	v_mul_f32_e32 v149, 0x3d372713, v148
	v_mul_f32_e32 v153, 0x3d372713, v152
	v_mul_f32_e32 v157, 0x3d372713, v156
	v_mul_f32_e32 v145, v145, v144
	v_mul_f32_e32 v149, v149, v148
	v_mul_f32_e32 v153, v153, v152
	v_mul_f32_e32 v157, v157, v156
	v_fma_f32 v146, v145, v144, v144
	v_fma_f32 v150, v149, v148, v148
	v_fma_f32 v154, v153, v152, v152
	v_fma_f32 v158, v157, v156, v156
	v_mul_f32_e32 v146, 0xc0135761, v146
	v_mul_f32_e32 v150, 0xc0135761, v150
	v_mul_f32_e32 v154, 0xc0135761, v154
	v_mul_f32_e32 v158, 0xc0135761, v158
	v_exp_f32_e32 v147, v146
	v_exp_f32_e32 v151, v150
	v_exp_f32_e32 v155, v154
	v_exp_f32_e32 v159, v158
	v_add_f32_e32 v147, 1.0, v147
	v_add_f32_e32 v151, 1.0, v151
	v_add_f32_e32 v155, 1.0, v155
	v_add_f32_e32 v159, 1.0, v159
	v_rcp_f32_e32 v147, v147
	v_rcp_f32_e32 v151, v151
	v_rcp_f32_e32 v155, v155
	v_rcp_f32_e32 v159, v159
	v_mul_f32_e32 v144, v144, v147
	v_mul_f32_e32 v148, v148, v151
	v_mul_f32_e32 v152, v152, v155
	v_mul_f32_e32 v156, v156, v159
	v_cvt_pk_bf16_f32 v145, v144, v144
	v_cvt_pk_bf16_f32 v149, v148, v148
	v_cvt_pk_bf16_f32 v153, v152, v152
	v_cvt_pk_bf16_f32 v157, v156, v156
	ds_write_b16 v194, v145 offset:512
	ds_write_b16 v194, v149 offset:544
	ds_write_b16 v194, v153 offset:576
	ds_write_b16 v194, v157 offset:608
	ds_read_b128 v[184:187], v195
	v_add_u32_e32 v196, 0x8000, v190
	s_waitcnt lgkmcnt(0)
	global_store_dwordx4 v196, v[184:187], s[6:7]
	v_add_u32_e32 v189, 0x400000, v189
	v_add_u32_e32 v190, 0x400000, v190
	s_add_i32 s86, s86, s87
	s_cmpk_gt_i32 s86, 0x3fff
	s_cbranch_scc0 .Lssm3_task
